# NA: bias tile in its own registers, LDS reads issued at tile top (no lgkmcnt(0) stall before the bias adds)
# baseline (speedup 1.0000x reference)
.Lna_wloop:
	s_sub_i32 s36, s24, s23
	s_cmp_lt_u32 s36, s63
	s_cselect_b64 s[40:41], -1, 0
	s_add_i32 s36, s36, 1
	s_cmp_lt_u32 s36, 8
	s_cselect_b64 s[44:45], -1, 0
	s_sub_i32 s37, s36, s62
	s_cmp_lt_u32 s37, 8
	s_cselect_b64 s[46:47], -1, 0
	s_and_b64 s[48:49], s[44:45], s[64:65]
	s_andn2_b64 s[38:39], s[46:47], s[64:65]
	s_or_b64 s[48:49], s[48:49], s[38:39]
	s_or_b64 s[42:43], s[44:45], s[46:47]
	s_and_b64 s[44:45], s[44:45], s[46:47]
	s_and_b64 s[44:45], s[44:45], s[40:41]
	s_cmp_eq_u64 s[44:45], 0
	s_cbranch_scc1 .Lna_slow_w1
	ds_read_b128 v[146:149], v199 offset:0
	ds_read_b128 v[150:153], v199 offset:32
	ds_read_b128 v[154:157], v199 offset:64
	ds_read_b128 v[158:161], v199 offset:96
	v_add_u32_e32 v210, s25, v208
	ds_read_b128 v[178:181], v210 offset:0
	ds_read_b128 v[182:185], v210 offset:32
	ds_read_b128 v[238:241], v210 offset:64
	ds_read_b128 v[242:245], v210 offset:96
	v_exp_f32_e32 v66, v66
	v_exp_f32_e32 v67, v67
	v_exp_f32_e32 v68, v68
	v_exp_f32_e32 v69, v69
	v_add_f32_e32 v213, v213, v66
	v_add_f32_e32 v214, v214, v67
	s_waitcnt lgkmcnt(7)
	v_mfma_f32_32x32x16_bf16 v[34:49], v[146:149], v[98:101], v[114:129]
	ds_read_b64 v[162:163], v201 offset:8704
	ds_read_b64 v[164:165], v201 offset:8720
	v_add_f32_e32 v213, v213, v68
	v_add_f32_e32 v214, v214, v69
	v_exp_f32_e32 v70, v70
	v_exp_f32_e32 v71, v71
	v_exp_f32_e32 v72, v72
	v_exp_f32_e32 v73, v73
	s_waitcnt lgkmcnt(8)
	v_mfma_f32_32x32x16_bf16 v[34:49], v[150:153], v[102:105], v[34:49]
	ds_read_b64 v[166:167], v201 offset:13056
	ds_read_b64 v[168:169], v201 offset:13072
	v_add_f32_e32 v213, v213, v70
	v_add_f32_e32 v214, v214, v71
	v_add_f32_e32 v213, v213, v72
	v_add_f32_e32 v214, v214, v73
	v_cvt_pk_bf16_f32 v66, v66, v67
	v_cvt_pk_bf16_f32 v67, v68, v69
	v_cvt_pk_bf16_f32 v68, v70, v71
	v_cvt_pk_bf16_f32 v69, v72, v73
	s_waitcnt lgkmcnt(9)
	v_mfma_f32_32x32x16_bf16 v[34:49], v[154:157], v[106:109], v[34:49]
	ds_read_b64 v[170:171], v201 offset:8736
	ds_read_b64 v[172:173], v201 offset:8752
	v_exp_f32_e32 v74, v74
	v_exp_f32_e32 v75, v75
	v_exp_f32_e32 v76, v76
	v_exp_f32_e32 v77, v77
	v_add_f32_e32 v213, v213, v74
	s_waitcnt lgkmcnt(10)
	v_mfma_f32_32x32x16_bf16 v[34:49], v[158:161], v[110:113], v[34:49]
	ds_read_b64 v[174:175], v201 offset:13088
	ds_read_b64 v[176:177], v201 offset:13104
	v_add_f32_e32 v214, v214, v75
	v_add_f32_e32 v213, v213, v76
	v_add_f32_e32 v214, v214, v77
	v_exp_f32_e32 v78, v78
	v_exp_f32_e32 v79, v79
	v_exp_f32_e32 v80, v80
	s_waitcnt lgkmcnt(6)
	v_mfma_f32_32x32x16_bf16 v[2:17], v[162:165], v[66:69], v[2:17]
	v_exp_f32_e32 v81, v81
	v_add_f32_e32 v213, v213, v78
	v_add_f32_e32 v214, v214, v79
	v_add_f32_e32 v213, v213, v80
	v_add_f32_e32 v214, v214, v81
	v_cvt_pk_bf16_f32 v74, v74, v75
	v_cvt_pk_bf16_f32 v75, v76, v77
	v_cvt_pk_bf16_f32 v76, v78, v79
	s_waitcnt lgkmcnt(4)
	v_mfma_f32_32x32x16_bf16 v[18:33], v[166:169], v[66:69], v[18:33]
	v_cvt_pk_bf16_f32 v77, v80, v81
	v_add_f32_e32 v34, v34, v178
	v_add_f32_e32 v35, v35, v179
	v_add_f32_e32 v36, v36, v180
	v_add_f32_e32 v37, v37, v181
	v_add_f32_e32 v38, v38, v182
	v_add_f32_e32 v39, v39, v183
	v_add_f32_e32 v40, v40, v184
	v_add_f32_e32 v41, v41, v185
	s_waitcnt lgkmcnt(2)
	v_mfma_f32_32x32x16_bf16 v[2:17], v[170:173], v[74:77], v[2:17]
	v_add_f32_e32 v42, v42, v238
	v_add_f32_e32 v43, v43, v239
	v_add_f32_e32 v44, v44, v240
	v_add_f32_e32 v45, v45, v241
	v_add_f32_e32 v46, v46, v242
	v_add_f32_e32 v47, v47, v243
	v_add_f32_e32 v48, v48, v244
	v_add_f32_e32 v49, v49, v245
	v_max3_f32 v216, v34, v35, v36
	s_waitcnt lgkmcnt(0)
	v_mfma_f32_32x32x16_bf16 v[18:33], v[174:177], v[74:77], v[18:33]
	s_waitcnt vmcnt(2)
	ds_write_b128 v204, v[230:233] offset:9216
	ds_write_b64 v205, v[234:235] offset:0
	ds_write_b64 v205, v[236:237] offset:8
	global_load_dwordx4 v[230:233], v206, s[12:13]
	s_add_i32 s20, s20, 1
	s_add_u32 s12, s12, 0x2000
	s_addc_u32 s13, s13, 0
	s_cmp_eq_u32 s20, s22
	s_cselect_b32 s12, s16, s12
	s_cselect_b32 s13, s17, s13
	global_load_dwordx4 v[234:237], v207, s[14:15]
	s_add_i32 s21, s21, 1
	s_add_u32 s14, s14, 0x80
	s_addc_u32 s15, s15, 0
	s_cmp_eq_u32 s21, s22
	s_cselect_b32 s14, s18, s14
	s_cselect_b32 s15, s19, s15
	v_max3_f32 v217, v42, v43, v44
	v_max3_f32 v216, v216, v37, v38
	v_max3_f32 v217, v217, v45, v46
	v_max3_f32 v216, v216, v39, v40
	v_max3_f32 v217, v217, v47, v48
	v_max_f32_e32 v216, v216, v41
	v_max_f32_e32 v217, v217, v49
	v_max_f32_e32 v216, v216, v217
	v_cmp_lt_f32_e32 vcc, 4.0, v216
	s_or_b64 s[28:29], vcc, s[26:27]
	s_cmp_lg_u64 s[28:29], 0
	s_cbranch_scc0 .Lna_nr_w1f
	v_mov_b32_e32 v217, v216
	s_nop 1
	v_permlane32_swap_b32_e32 v216, v217
	v_max_f32_e32 v215, v216, v217
	s_nop 15
	v_max_f32_e32 v216, v215, v220
	v_cmp_lt_f32_e32 vcc, 0xf0c9f2ca, v215
	s_nop 1
	v_cndmask_b32_e32 v216, 0, v216, vcc
	v_exp_f32_e64 v217, -v216
	v_add_f32_e32 v212, v212, v216
	v_and_b32_e32 v217, v217, v221
	v_sub_f32_e32 v34, v34, v216
	v_sub_f32_e32 v35, v35, v216
	v_sub_f32_e32 v36, v36, v216
	v_sub_f32_e32 v37, v37, v216
	v_sub_f32_e32 v38, v38, v216
	v_sub_f32_e32 v39, v39, v216
	v_sub_f32_e32 v40, v40, v216
	v_sub_f32_e32 v41, v41, v216
	v_sub_f32_e32 v42, v42, v216
	v_sub_f32_e32 v43, v43, v216
	v_sub_f32_e32 v44, v44, v216
	v_sub_f32_e32 v45, v45, v216
	v_sub_f32_e32 v46, v46, v216
	v_sub_f32_e32 v47, v47, v216
	v_sub_f32_e32 v48, v48, v216
	v_sub_f32_e32 v49, v49, v216
	v_sub_f32_e32 v114, v114, v216
	v_sub_f32_e32 v115, v115, v216
	v_sub_f32_e32 v116, v116, v216
	v_sub_f32_e32 v117, v117, v216
	v_sub_f32_e32 v118, v118, v216
	v_sub_f32_e32 v119, v119, v216
	v_sub_f32_e32 v120, v120, v216
	v_sub_f32_e32 v121, v121, v216
	v_sub_f32_e32 v122, v122, v216
	v_sub_f32_e32 v123, v123, v216
	v_sub_f32_e32 v124, v124, v216
	v_sub_f32_e32 v125, v125, v216
	v_sub_f32_e32 v126, v126, v216
	v_sub_f32_e32 v127, v127, v216
	v_sub_f32_e32 v128, v128, v216
	v_sub_f32_e32 v129, v129, v216
	v_mul_f32_e32 v213, v213, v217
	v_mul_f32_e32 v214, v214, v217
	v_mul_f32_e32 v2, v2, v217
	v_mul_f32_e32 v3, v3, v217
	v_mul_f32_e32 v4, v4, v217
	v_mul_f32_e32 v5, v5, v217
	v_mul_f32_e32 v6, v6, v217
	v_mul_f32_e32 v7, v7, v217
	v_mul_f32_e32 v8, v8, v217
	v_mul_f32_e32 v9, v9, v217
	v_mul_f32_e32 v10, v10, v217
	v_mul_f32_e32 v11, v11, v217
	v_mul_f32_e32 v12, v12, v217
	v_mul_f32_e32 v13, v13, v217
	v_mul_f32_e32 v14, v14, v217
	v_mul_f32_e32 v15, v15, v217
	v_mul_f32_e32 v16, v16, v217
	v_mul_f32_e32 v17, v17, v217
	v_mul_f32_e32 v18, v18, v217
	v_mul_f32_e32 v19, v19, v217
	v_mul_f32_e32 v20, v20, v217
	v_mul_f32_e32 v21, v21, v217
	v_mul_f32_e32 v22, v22, v217
	v_mul_f32_e32 v23, v23, v217
	v_mul_f32_e32 v24, v24, v217
	v_mul_f32_e32 v25, v25, v217
	v_mul_f32_e32 v26, v26, v217
	v_mul_f32_e32 v27, v27, v217
	v_mul_f32_e32 v28, v28, v217
	v_mul_f32_e32 v29, v29, v217
	v_mul_f32_e32 v30, v30, v217
	v_mul_f32_e32 v31, v31, v217
	v_mul_f32_e32 v32, v32, v217
	v_mul_f32_e32 v33, v33, v217
	v_cndmask_b32_e32 v220, v220, v228, vcc
	v_cndmask_b32_e64 v221, v221, -1, vcc
	s_andn2_b64 s[26:27], s[26:27], vcc

.Lna_sl_a_w1s:
	s_waitcnt lgkmcnt(0)
	s_cmp_eq_u64 s[42:43], 0
	s_cbranch_scc1 .Lna_sl_b_w1s
	ds_read_b128 v[146:149], v199 offset:0
	ds_read_b128 v[150:153], v199 offset:32
	ds_read_b128 v[154:157], v199 offset:64
	ds_read_b128 v[158:161], v199 offset:96
	s_waitcnt lgkmcnt(3)
	v_mfma_f32_32x32x16_bf16 v[34:49], v[146:149], v[98:101], v[114:129]
	s_waitcnt lgkmcnt(2)
	v_mfma_f32_32x32x16_bf16 v[34:49], v[150:153], v[102:105], v[34:49]
	s_waitcnt lgkmcnt(1)
	v_mfma_f32_32x32x16_bf16 v[34:49], v[154:157], v[106:109], v[34:49]
	s_waitcnt lgkmcnt(0)
	v_mfma_f32_32x32x16_bf16 v[34:49], v[158:161], v[110:113], v[34:49]
	v_add_u32_e32 v210, s25, v208
	ds_read_b128 v[178:181], v210 offset:0
	ds_read_b128 v[182:185], v210 offset:32
	ds_read_b128 v[238:241], v210 offset:64
	ds_read_b128 v[242:245], v210 offset:96
	s_waitcnt lgkmcnt(0)
	s_nop 15
	v_add_f32_e32 v34, v34, v178
	v_add_f32_e32 v35, v35, v179
	v_add_f32_e32 v36, v36, v180
	v_add_f32_e32 v37, v37, v181
	v_add_f32_e32 v38, v38, v182
	v_add_f32_e32 v39, v39, v183
	v_add_f32_e32 v40, v40, v184
	v_add_f32_e32 v41, v41, v185
	v_add_f32_e32 v42, v42, v238
	v_add_f32_e32 v43, v43, v239
	v_add_f32_e32 v44, v44, v240
	v_add_f32_e32 v45, v45, v241
	v_add_f32_e32 v46, v46, v242
	v_add_f32_e32 v47, v47, v243
	v_add_f32_e32 v48, v48, v244
	v_add_f32_e32 v49, v49, v245
	v_cndmask_b32_e64 v34, v229, v34, s[48:49]
	v_cndmask_b32_e64 v35, v229, v35, s[48:49]
	v_cndmask_b32_e64 v36, v229, v36, s[48:49]
	v_cndmask_b32_e64 v37, v229, v37, s[48:49]
	v_cndmask_b32_e64 v38, v229, v38, s[48:49]
	v_cndmask_b32_e64 v39, v229, v39, s[48:49]
	v_cndmask_b32_e64 v40, v229, v40, s[48:49]
	v_cndmask_b32_e64 v41, v229, v41, s[48:49]
	v_cndmask_b32_e64 v42, v229, v42, s[48:49]
	v_cndmask_b32_e64 v43, v229, v43, s[48:49]
	v_cndmask_b32_e64 v44, v229, v44, s[48:49]
	v_cndmask_b32_e64 v45, v229, v45, s[48:49]
	v_cndmask_b32_e64 v46, v229, v46, s[48:49]
	v_cndmask_b32_e64 v47, v229, v47, s[48:49]
	v_cndmask_b32_e64 v48, v229, v48, s[48:49]
	v_cndmask_b32_e64 v49, v229, v49, s[48:49]
	v_max3_f32 v216, v34, v35, v36
	v_max3_f32 v217, v42, v43, v44
	v_max3_f32 v216, v216, v37, v38
	v_max3_f32 v217, v217, v45, v46
	v_max3_f32 v216, v216, v39, v40
	v_max3_f32 v217, v217, v47, v48
	v_max_f32_e32 v216, v216, v41
	v_max_f32_e32 v217, v217, v49
	v_max_f32_e32 v216, v216, v217
	v_cmp_lt_f32_e32 vcc, 4.0, v216
	s_or_b64 s[28:29], vcc, s[26:27]
	s_cmp_lg_u64 s[28:29], 0
	s_cbranch_scc0 .Lna_nr_w1s
	v_mov_b32_e32 v217, v216
	s_nop 1
	v_permlane32_swap_b32_e32 v216, v217
	v_max_f32_e32 v215, v216, v217
	s_nop 15
	v_max_f32_e32 v216, v215, v220
	v_cmp_lt_f32_e32 vcc, 0xf0c9f2ca, v215
	s_nop 1
	v_cndmask_b32_e32 v216, 0, v216, vcc
	v_exp_f32_e64 v217, -v216
	v_add_f32_e32 v212, v212, v216
	v_and_b32_e32 v217, v217, v221
	v_sub_f32_e32 v34, v34, v216
	v_sub_f32_e32 v35, v35, v216
	v_sub_f32_e32 v36, v36, v216
	v_sub_f32_e32 v37, v37, v216
	v_sub_f32_e32 v38, v38, v216
	v_sub_f32_e32 v39, v39, v216
	v_sub_f32_e32 v40, v40, v216
	v_sub_f32_e32 v41, v41, v216
	v_sub_f32_e32 v42, v42, v216
	v_sub_f32_e32 v43, v43, v216
	v_sub_f32_e32 v44, v44, v216
	v_sub_f32_e32 v45, v45, v216
	v_sub_f32_e32 v46, v46, v216
	v_sub_f32_e32 v47, v47, v216
	v_sub_f32_e32 v48, v48, v216
	v_sub_f32_e32 v49, v49, v216
	v_sub_f32_e32 v114, v114, v216
	v_sub_f32_e32 v115, v115, v216
	v_sub_f32_e32 v116, v116, v216
	v_sub_f32_e32 v117, v117, v216
	v_sub_f32_e32 v118, v118, v216
	v_sub_f32_e32 v119, v119, v216
	v_sub_f32_e32 v120, v120, v216
	v_sub_f32_e32 v121, v121, v216
	v_sub_f32_e32 v122, v122, v216
	v_sub_f32_e32 v123, v123, v216
	v_sub_f32_e32 v124, v124, v216
	v_sub_f32_e32 v125, v125, v216
	v_sub_f32_e32 v126, v126, v216
	v_sub_f32_e32 v127, v127, v216
	v_sub_f32_e32 v128, v128, v216
	v_sub_f32_e32 v129, v129, v216
	v_mul_f32_e32 v213, v213, v217
	v_mul_f32_e32 v214, v214, v217
	v_mul_f32_e32 v2, v2, v217
	v_mul_f32_e32 v3, v3, v217
	v_mul_f32_e32 v4, v4, v217
	v_mul_f32_e32 v5, v5, v217
	v_mul_f32_e32 v6, v6, v217
	v_mul_f32_e32 v7, v7, v217
	v_mul_f32_e32 v8, v8, v217
	v_mul_f32_e32 v9, v9, v217
	v_mul_f32_e32 v10, v10, v217
	v_mul_f32_e32 v11, v11, v217
	v_mul_f32_e32 v12, v12, v217
	v_mul_f32_e32 v13, v13, v217
	v_mul_f32_e32 v14, v14, v217
	v_mul_f32_e32 v15, v15, v217
	v_mul_f32_e32 v16, v16, v217
	v_mul_f32_e32 v17, v17, v217
	v_mul_f32_e32 v18, v18, v217
	v_mul_f32_e32 v19, v19, v217
	v_mul_f32_e32 v20, v20, v217
	v_mul_f32_e32 v21, v21, v217
	v_mul_f32_e32 v22, v22, v217
	v_mul_f32_e32 v23, v23, v217
	v_mul_f32_e32 v24, v24, v217
	v_mul_f32_e32 v25, v25, v217
	v_mul_f32_e32 v26, v26, v217
	v_mul_f32_e32 v27, v27, v217
	v_mul_f32_e32 v28, v28, v217
	v_mul_f32_e32 v29, v29, v217
	v_mul_f32_e32 v30, v30, v217
	v_mul_f32_e32 v31, v31, v217
	v_mul_f32_e32 v32, v32, v217
	v_mul_f32_e32 v33, v33, v217
	v_cndmask_b32_e32 v220, v220, v228, vcc
	v_cndmask_b32_e64 v221, v221, -1, vcc
	s_andn2_b64 s[26:27], s[26:27], vcc

.Lna_done_w1:
	s_add_i32 s24, s24, 1
	s_add_i32 s25, s25, 0x150
	s_sub_i32 s36, s24, s23
	s_cmp_lt_u32 s36, s63
	s_cselect_b64 s[40:41], -1, 0
	s_add_i32 s36, s36, 1
	s_cmp_lt_u32 s36, 8
	s_cselect_b64 s[44:45], -1, 0
	s_sub_i32 s37, s36, s62
	s_cmp_lt_u32 s37, 8
	s_cselect_b64 s[46:47], -1, 0
	s_and_b64 s[48:49], s[44:45], s[64:65]
	s_andn2_b64 s[38:39], s[46:47], s[64:65]
	s_or_b64 s[48:49], s[48:49], s[38:39]
	s_or_b64 s[42:43], s[44:45], s[46:47]
	s_and_b64 s[44:45], s[44:45], s[46:47]
	s_and_b64 s[44:45], s[44:45], s[40:41]
	s_cmp_eq_u64 s[44:45], 0
	s_cbranch_scc1 .Lna_slow_w0
	ds_read_b128 v[146:149], v199 offset:9216
	ds_read_b128 v[150:153], v199 offset:9248
	ds_read_b128 v[154:157], v199 offset:9280
	ds_read_b128 v[158:161], v199 offset:9312
	v_add_u32_e32 v210, s25, v208
	ds_read_b128 v[178:181], v210 offset:0
	ds_read_b128 v[182:185], v210 offset:32
	ds_read_b128 v[238:241], v210 offset:64
	ds_read_b128 v[242:245], v210 offset:96
	v_exp_f32_e32 v34, v34
	v_exp_f32_e32 v35, v35
	v_exp_f32_e32 v36, v36
	v_exp_f32_e32 v37, v37
	v_add_f32_e32 v213, v213, v34
	v_add_f32_e32 v214, v214, v35
	s_waitcnt lgkmcnt(7)
	v_mfma_f32_32x32x16_bf16 v[66:81], v[146:149], v[98:101], v[114:129]
	ds_read_b64 v[162:163], v201 offset:0
	ds_read_b64 v[164:165], v201 offset:16
	v_add_f32_e32 v213, v213, v36
	v_add_f32_e32 v214, v214, v37
	v_exp_f32_e32 v38, v38
	v_exp_f32_e32 v39, v39
	v_exp_f32_e32 v40, v40
	v_exp_f32_e32 v41, v41
	s_waitcnt lgkmcnt(8)
	v_mfma_f32_32x32x16_bf16 v[66:81], v[150:153], v[102:105], v[66:81]
	ds_read_b64 v[166:167], v201 offset:4352
	ds_read_b64 v[168:169], v201 offset:4368
	v_add_f32_e32 v213, v213, v38
	v_add_f32_e32 v214, v214, v39
	v_add_f32_e32 v213, v213, v40
	v_add_f32_e32 v214, v214, v41
	v_cvt_pk_bf16_f32 v34, v34, v35
	v_cvt_pk_bf16_f32 v35, v36, v37
	v_cvt_pk_bf16_f32 v36, v38, v39
	v_cvt_pk_bf16_f32 v37, v40, v41
	s_waitcnt lgkmcnt(9)
	v_mfma_f32_32x32x16_bf16 v[66:81], v[154:157], v[106:109], v[66:81]
	ds_read_b64 v[170:171], v201 offset:32
	ds_read_b64 v[172:173], v201 offset:48
	v_exp_f32_e32 v42, v42
	v_exp_f32_e32 v43, v43
	v_exp_f32_e32 v44, v44
	v_exp_f32_e32 v45, v45
	v_add_f32_e32 v213, v213, v42
	s_waitcnt lgkmcnt(10)
	v_mfma_f32_32x32x16_bf16 v[66:81], v[158:161], v[110:113], v[66:81]
	ds_read_b64 v[174:175], v201 offset:4384
	ds_read_b64 v[176:177], v201 offset:4400
	v_add_f32_e32 v214, v214, v43
	v_add_f32_e32 v213, v213, v44
	v_add_f32_e32 v214, v214, v45
	v_exp_f32_e32 v46, v46
	v_exp_f32_e32 v47, v47
	v_exp_f32_e32 v48, v48
	s_waitcnt lgkmcnt(6)
	v_mfma_f32_32x32x16_bf16 v[2:17], v[162:165], v[34:37], v[2:17]
	v_exp_f32_e32 v49, v49
	v_add_f32_e32 v213, v213, v46
	v_add_f32_e32 v214, v214, v47
	v_add_f32_e32 v213, v213, v48
	v_add_f32_e32 v214, v214, v49
	v_cvt_pk_bf16_f32 v42, v42, v43
	v_cvt_pk_bf16_f32 v43, v44, v45
	v_cvt_pk_bf16_f32 v44, v46, v47
	s_waitcnt lgkmcnt(4)
	v_mfma_f32_32x32x16_bf16 v[18:33], v[166:169], v[34:37], v[18:33]
	v_cvt_pk_bf16_f32 v45, v48, v49
	v_add_f32_e32 v66, v66, v178
	v_add_f32_e32 v67, v67, v179
	v_add_f32_e32 v68, v68, v180
	v_add_f32_e32 v69, v69, v181
	v_add_f32_e32 v70, v70, v182
	v_add_f32_e32 v71, v71, v183
	v_add_f32_e32 v72, v72, v184
	v_add_f32_e32 v73, v73, v185
	s_waitcnt lgkmcnt(2)
	v_mfma_f32_32x32x16_bf16 v[2:17], v[170:173], v[42:45], v[2:17]
	v_add_f32_e32 v74, v74, v238
	v_add_f32_e32 v75, v75, v239
	v_add_f32_e32 v76, v76, v240
	v_add_f32_e32 v77, v77, v241
	v_add_f32_e32 v78, v78, v242
	v_add_f32_e32 v79, v79, v243
	v_add_f32_e32 v80, v80, v244
	v_add_f32_e32 v81, v81, v245
	v_max3_f32 v216, v66, v67, v68
	s_waitcnt lgkmcnt(0)
	v_mfma_f32_32x32x16_bf16 v[18:33], v[174:177], v[42:45], v[18:33]
	s_waitcnt vmcnt(2)
	ds_write_b128 v204, v[188:191] offset:0
	ds_write_b64 v205, v[192:193] offset:8704
	ds_write_b64 v205, v[194:195] offset:8712
	global_load_dwordx4 v[188:191], v206, s[12:13]
	s_add_i32 s20, s20, 1
	s_add_u32 s12, s12, 0x2000
	s_addc_u32 s13, s13, 0
	s_cmp_eq_u32 s20, s22
	s_cselect_b32 s12, s16, s12
	s_cselect_b32 s13, s17, s13
	global_load_dwordx4 v[192:195], v207, s[14:15]
	s_add_i32 s21, s21, 1
	s_add_u32 s14, s14, 0x80
	s_addc_u32 s15, s15, 0
	s_cmp_eq_u32 s21, s22
	s_cselect_b32 s14, s18, s14
	s_cselect_b32 s15, s19, s15
	v_max3_f32 v217, v74, v75, v76
	v_max3_f32 v216, v216, v69, v70
	v_max3_f32 v217, v217, v77, v78
	v_max3_f32 v216, v216, v71, v72
	v_max3_f32 v217, v217, v79, v80
	v_max_f32_e32 v216, v216, v73
	v_max_f32_e32 v217, v217, v81
	v_max_f32_e32 v216, v216, v217
	v_cmp_lt_f32_e32 vcc, 4.0, v216
	s_or_b64 s[28:29], vcc, s[26:27]
	s_cmp_lg_u64 s[28:29], 0
	s_cbranch_scc0 .Lna_nr_w0f
	v_mov_b32_e32 v217, v216
	s_nop 1
	v_permlane32_swap_b32_e32 v216, v217
	v_max_f32_e32 v215, v216, v217
	s_nop 15
	v_max_f32_e32 v216, v215, v220
	v_cmp_lt_f32_e32 vcc, 0xf0c9f2ca, v215
	s_nop 1
	v_cndmask_b32_e32 v216, 0, v216, vcc
	v_exp_f32_e64 v217, -v216
	v_add_f32_e32 v212, v212, v216
	v_and_b32_e32 v217, v217, v221
	v_sub_f32_e32 v66, v66, v216
	v_sub_f32_e32 v67, v67, v216
	v_sub_f32_e32 v68, v68, v216
	v_sub_f32_e32 v69, v69, v216
	v_sub_f32_e32 v70, v70, v216
	v_sub_f32_e32 v71, v71, v216
	v_sub_f32_e32 v72, v72, v216
	v_sub_f32_e32 v73, v73, v216
	v_sub_f32_e32 v74, v74, v216
	v_sub_f32_e32 v75, v75, v216
	v_sub_f32_e32 v76, v76, v216
	v_sub_f32_e32 v77, v77, v216
	v_sub_f32_e32 v78, v78, v216
	v_sub_f32_e32 v79, v79, v216
	v_sub_f32_e32 v80, v80, v216
	v_sub_f32_e32 v81, v81, v216
	v_sub_f32_e32 v114, v114, v216
	v_sub_f32_e32 v115, v115, v216
	v_sub_f32_e32 v116, v116, v216
	v_sub_f32_e32 v117, v117, v216
	v_sub_f32_e32 v118, v118, v216
	v_sub_f32_e32 v119, v119, v216
	v_sub_f32_e32 v120, v120, v216
	v_sub_f32_e32 v121, v121, v216
	v_sub_f32_e32 v122, v122, v216
	v_sub_f32_e32 v123, v123, v216
	v_sub_f32_e32 v124, v124, v216
	v_sub_f32_e32 v125, v125, v216
	v_sub_f32_e32 v126, v126, v216
	v_sub_f32_e32 v127, v127, v216
	v_sub_f32_e32 v128, v128, v216
	v_sub_f32_e32 v129, v129, v216
	v_mul_f32_e32 v213, v213, v217
	v_mul_f32_e32 v214, v214, v217
	v_mul_f32_e32 v2, v2, v217
	v_mul_f32_e32 v3, v3, v217
	v_mul_f32_e32 v4, v4, v217
	v_mul_f32_e32 v5, v5, v217
	v_mul_f32_e32 v6, v6, v217
	v_mul_f32_e32 v7, v7, v217
	v_mul_f32_e32 v8, v8, v217
	v_mul_f32_e32 v9, v9, v217
	v_mul_f32_e32 v10, v10, v217
	v_mul_f32_e32 v11, v11, v217
	v_mul_f32_e32 v12, v12, v217
	v_mul_f32_e32 v13, v13, v217
	v_mul_f32_e32 v14, v14, v217
	v_mul_f32_e32 v15, v15, v217
	v_mul_f32_e32 v16, v16, v217
	v_mul_f32_e32 v17, v17, v217
	v_mul_f32_e32 v18, v18, v217
	v_mul_f32_e32 v19, v19, v217
	v_mul_f32_e32 v20, v20, v217
	v_mul_f32_e32 v21, v21, v217
	v_mul_f32_e32 v22, v22, v217
	v_mul_f32_e32 v23, v23, v217
	v_mul_f32_e32 v24, v24, v217
	v_mul_f32_e32 v25, v25, v217
	v_mul_f32_e32 v26, v26, v217
	v_mul_f32_e32 v27, v27, v217
	v_mul_f32_e32 v28, v28, v217
	v_mul_f32_e32 v29, v29, v217
	v_mul_f32_e32 v30, v30, v217
	v_mul_f32_e32 v31, v31, v217
	v_mul_f32_e32 v32, v32, v217
	v_mul_f32_e32 v33, v33, v217
	v_cndmask_b32_e32 v220, v220, v228, vcc
	v_cndmask_b32_e64 v221, v221, -1, vcc
	s_andn2_b64 s[26:27], s[26:27], vcc

.Lna_sl_a_w0s:
	s_waitcnt lgkmcnt(0)
	s_cmp_eq_u64 s[42:43], 0
	s_cbranch_scc1 .Lna_sl_b_w0s
	ds_read_b128 v[146:149], v199 offset:9216
	ds_read_b128 v[150:153], v199 offset:9248
	ds_read_b128 v[154:157], v199 offset:9280
	ds_read_b128 v[158:161], v199 offset:9312
	s_waitcnt lgkmcnt(3)
	v_mfma_f32_32x32x16_bf16 v[66:81], v[146:149], v[98:101], v[114:129]
	s_waitcnt lgkmcnt(2)
	v_mfma_f32_32x32x16_bf16 v[66:81], v[150:153], v[102:105], v[66:81]
	s_waitcnt lgkmcnt(1)
	v_mfma_f32_32x32x16_bf16 v[66:81], v[154:157], v[106:109], v[66:81]
	s_waitcnt lgkmcnt(0)
	v_mfma_f32_32x32x16_bf16 v[66:81], v[158:161], v[110:113], v[66:81]
	v_add_u32_e32 v210, s25, v208
	ds_read_b128 v[178:181], v210 offset:0
	ds_read_b128 v[182:185], v210 offset:32
	ds_read_b128 v[238:241], v210 offset:64
	ds_read_b128 v[242:245], v210 offset:96
	s_waitcnt lgkmcnt(0)
	s_nop 15
	v_add_f32_e32 v66, v66, v178
	v_add_f32_e32 v67, v67, v179
	v_add_f32_e32 v68, v68, v180
	v_add_f32_e32 v69, v69, v181
	v_add_f32_e32 v70, v70, v182
	v_add_f32_e32 v71, v71, v183
	v_add_f32_e32 v72, v72, v184
	v_add_f32_e32 v73, v73, v185
	v_add_f32_e32 v74, v74, v238
	v_add_f32_e32 v75, v75, v239
	v_add_f32_e32 v76, v76, v240
	v_add_f32_e32 v77, v77, v241
	v_add_f32_e32 v78, v78, v242
	v_add_f32_e32 v79, v79, v243
	v_add_f32_e32 v80, v80, v244
	v_add_f32_e32 v81, v81, v245
	v_cndmask_b32_e64 v66, v229, v66, s[48:49]
	v_cndmask_b32_e64 v67, v229, v67, s[48:49]
	v_cndmask_b32_e64 v68, v229, v68, s[48:49]
	v_cndmask_b32_e64 v69, v229, v69, s[48:49]
	v_cndmask_b32_e64 v70, v229, v70, s[48:49]
	v_cndmask_b32_e64 v71, v229, v71, s[48:49]
	v_cndmask_b32_e64 v72, v229, v72, s[48:49]
	v_cndmask_b32_e64 v73, v229, v73, s[48:49]
	v_cndmask_b32_e64 v74, v229, v74, s[48:49]
	v_cndmask_b32_e64 v75, v229, v75, s[48:49]
	v_cndmask_b32_e64 v76, v229, v76, s[48:49]
	v_cndmask_b32_e64 v77, v229, v77, s[48:49]
	v_cndmask_b32_e64 v78, v229, v78, s[48:49]
	v_cndmask_b32_e64 v79, v229, v79, s[48:49]
	v_cndmask_b32_e64 v80, v229, v80, s[48:49]
	v_cndmask_b32_e64 v81, v229, v81, s[48:49]
	v_max3_f32 v216, v66, v67, v68
	v_max3_f32 v217, v74, v75, v76
	v_max3_f32 v216, v216, v69, v70
	v_max3_f32 v217, v217, v77, v78
	v_max3_f32 v216, v216, v71, v72
	v_max3_f32 v217, v217, v79, v80
	v_max_f32_e32 v216, v216, v73
	v_max_f32_e32 v217, v217, v81
	v_max_f32_e32 v216, v216, v217
	v_cmp_lt_f32_e32 vcc, 4.0, v216
	s_or_b64 s[28:29], vcc, s[26:27]
	s_cmp_lg_u64 s[28:29], 0
	s_cbranch_scc0 .Lna_nr_w0s
	v_mov_b32_e32 v217, v216
	s_nop 1
	v_permlane32_swap_b32_e32 v216, v217
	v_max_f32_e32 v215, v216, v217
	s_nop 15
	v_max_f32_e32 v216, v215, v220
	v_cmp_lt_f32_e32 vcc, 0xf0c9f2ca, v215
	s_nop 1
	v_cndmask_b32_e32 v216, 0, v216, vcc
	v_exp_f32_e64 v217, -v216
	v_add_f32_e32 v212, v212, v216
	v_and_b32_e32 v217, v217, v221
	v_sub_f32_e32 v66, v66, v216
	v_sub_f32_e32 v67, v67, v216
	v_sub_f32_e32 v68, v68, v216
	v_sub_f32_e32 v69, v69, v216
	v_sub_f32_e32 v70, v70, v216
	v_sub_f32_e32 v71, v71, v216
	v_sub_f32_e32 v72, v72, v216
	v_sub_f32_e32 v73, v73, v216
	v_sub_f32_e32 v74, v74, v216
	v_sub_f32_e32 v75, v75, v216
	v_sub_f32_e32 v76, v76, v216
	v_sub_f32_e32 v77, v77, v216
	v_sub_f32_e32 v78, v78, v216
	v_sub_f32_e32 v79, v79, v216
	v_sub_f32_e32 v80, v80, v216
	v_sub_f32_e32 v81, v81, v216
	v_sub_f32_e32 v114, v114, v216
	v_sub_f32_e32 v115, v115, v216
	v_sub_f32_e32 v116, v116, v216
	v_sub_f32_e32 v117, v117, v216
	v_sub_f32_e32 v118, v118, v216
	v_sub_f32_e32 v119, v119, v216
	v_sub_f32_e32 v120, v120, v216
	v_sub_f32_e32 v121, v121, v216
	v_sub_f32_e32 v122, v122, v216
	v_sub_f32_e32 v123, v123, v216
	v_sub_f32_e32 v124, v124, v216
	v_sub_f32_e32 v125, v125, v216
	v_sub_f32_e32 v126, v126, v216
	v_sub_f32_e32 v127, v127, v216
	v_sub_f32_e32 v128, v128, v216
	v_sub_f32_e32 v129, v129, v216
	v_mul_f32_e32 v213, v213, v217
	v_mul_f32_e32 v214, v214, v217
	v_mul_f32_e32 v2, v2, v217
	v_mul_f32_e32 v3, v3, v217
	v_mul_f32_e32 v4, v4, v217
	v_mul_f32_e32 v5, v5, v217
	v_mul_f32_e32 v6, v6, v217
	v_mul_f32_e32 v7, v7, v217
	v_mul_f32_e32 v8, v8, v217
	v_mul_f32_e32 v9, v9, v217
	v_mul_f32_e32 v10, v10, v217
	v_mul_f32_e32 v11, v11, v217
	v_mul_f32_e32 v12, v12, v217
	v_mul_f32_e32 v13, v13, v217
	v_mul_f32_e32 v14, v14, v217
	v_mul_f32_e32 v15, v15, v217
	v_mul_f32_e32 v16, v16, v217
	v_mul_f32_e32 v17, v17, v217
	v_mul_f32_e32 v18, v18, v217
	v_mul_f32_e32 v19, v19, v217
	v_mul_f32_e32 v20, v20, v217
	v_mul_f32_e32 v21, v21, v217
	v_mul_f32_e32 v22, v22, v217
	v_mul_f32_e32 v23, v23, v217
	v_mul_f32_e32 v24, v24, v217
	v_mul_f32_e32 v25, v25, v217
	v_mul_f32_e32 v26, v26, v217
	v_mul_f32_e32 v27, v27, v217
	v_mul_f32_e32 v28, v28, v217
	v_mul_f32_e32 v29, v29, v217
	v_mul_f32_e32 v30, v30, v217
	v_mul_f32_e32 v31, v31, v217
	v_mul_f32_e32 v32, v32, v217
	v_mul_f32_e32 v33, v33, v217
	v_cndmask_b32_e32 v220, v220, v228, vcc
	v_cndmask_b32_e64 v221, v221, -1, vcc
	s_andn2_b64 s[26:27], s[26:27], vcc
